# P0 x-row loop: non-temporal (nt) hint on the read-once f32 x row loads
# speedup vs baseline: 1.0182x; 1.0182x over previous
.LBB0_161:
	s_waitcnt lgkmcnt(0)
	global_load_dwordx4 v[12:15], v[4:5], off offset:-3072 nt
	global_load_dwordx4 v[16:19], v[4:5], off offset:-2048 nt
	global_load_dwordx4 v[20:23], v[4:5], off offset:-1024 nt
	global_load_dwordx4 v[24:27], v[4:5], off nt
	s_waitcnt vmcnt(3)
	v_mul_f32_e32 v2, v13, v13
	v_mul_f32_e32 v28, v15, v15
	s_waitcnt vmcnt(2)
	v_mul_f32_e32 v29, v17, v17
	v_mul_f32_e32 v30, v19, v19
	s_waitcnt vmcnt(1)
	v_mul_f32_e32 v31, v21, v21
	v_mul_f32_e32 v32, v23, v23
	v_fmac_f32_e32 v2, v12, v12
	v_fmac_f32_e32 v28, v14, v14
	v_fmac_f32_e32 v29, v16, v16
	v_fmac_f32_e32 v30, v18, v18
	s_waitcnt vmcnt(0)
	v_mul_f32_e32 v33, v25, v25
	v_mul_f32_e32 v34, v27, v27
	v_fmac_f32_e32 v31, v20, v20
	v_fmac_f32_e32 v32, v22, v22
	v_add_f32_e32 v2, v2, v28
	v_add_f32_e32 v28, v29, v30
	v_fmac_f32_e32 v33, v24, v24
	v_fmac_f32_e32 v34, v26, v26
	v_add_f32_e32 v29, v31, v32
	v_add_f32_e32 v2, v2, v28
	v_add_f32_e32 v30, v33, v34
	v_add_f32_e32 v2, v2, v29
	v_add_f32_e32 v2, v2, v30
	ds_bpermute_b32 v28, v6, v2
	v_cvt_pk_bf16_f32 v12, v12, v13
	v_cvt_pk_bf16_f32 v13, v14, v15
	v_cvt_pk_bf16_f32 v14, v16, v17
	v_cvt_pk_bf16_f32 v15, v18, v19
	s_waitcnt lgkmcnt(0)
	v_add_f32_e32 v2, v2, v28
	ds_bpermute_b32 v28, v7, v2
	v_cvt_pk_bf16_f32 v16, v20, v21
	s_waitcnt lgkmcnt(0)
	v_add_f32_e32 v2, v2, v28
	ds_bpermute_b32 v30, v8, v2
	v_lshl_add_u64 v[28:29], s[96:97], 0, v[0:1]
	v_add_co_u32_e64 v28, s[0:1], s9, v28
	s_waitcnt lgkmcnt(0)
	v_add_f32_e32 v2, v2, v30
	ds_bpermute_b32 v30, v9, v2
	v_addc_co_u32_e64 v29, s[0:1], 0, v29, s[0:1]
	global_store_dwordx2 v[28:29], v[12:13], off
	global_store_dwordx2 v[28:29], v[14:15], off offset:512
	v_cvt_pk_bf16_f32 v14, v24, v25
	s_waitcnt lgkmcnt(0)
	v_add_f32_e32 v2, v2, v30
	ds_bpermute_b32 v17, v10, v2
	v_cvt_pk_bf16_f32 v15, v26, v27
	global_store_dwordx2 v[28:29], v[14:15], off offset:1536
	s_waitcnt lgkmcnt(0)
	v_add_f32_e32 v2, v2, v17
	ds_bpermute_b32 v12, v11, v2
	v_cvt_pk_bf16_f32 v17, v22, v23
	global_store_dwordx2 v[28:29], v[16:17], off offset:1024
	s_and_saveexec_b64 s[0:1], vcc
	s_cbranch_execz .LBB0_160
	s_add_u32 s16, s96, s2
	s_addc_u32 s17, s97, s3
	s_waitcnt lgkmcnt(0)
	v_add_f32_e32 v2, v2, v12
	global_store_dword v3, v2, s[16:17]
	s_branch .LBB0_160
